# P5: prefetch next token's xn row during fp8 conversion of the current one (A step), on top of sorted round-major u-pass
# speedup vs baseline: 1.0959x; 1.0066x over previous
; __device__ __forceinline__ void peer_stage2_batch(const Params& P, int tbase, int tstride, int lane, unsigned char* res, unsigned char* scr) {
;     ...
;     int* sid = (int*)(res + tau * 1024) + hd * 16; float* sgate = (float*)(res + tau * 1024 + 512) + hd * 16;
; #pragma unroll
;     for (int q = 0; q < 4; ++q) {
;         *(int4*)(sid + 4 * q) = make_int4(ids[4 * q], ids[4 * q + 1], ids[4 * q + 2], ids[4 * q + 3]);
;         *(float4*)(sgate + 4 * q) = make_float4(e[4 * q] * inv, e[4 * q + 1] * inv, e[4 * q + 2] * inv, e[4 * q + 3] * inv);
;     }
; __device__ __forceinline__ void peer_token(const Params& P, int t, int lane, int* sidx, float* sval, const int* sid, const float* sgate, const unsigned* szero) {
;     const bf16_t* xn = (const bf16_t*)(P.ws + WS_XN) + (size_t)t * DM;
;     const uint4 xa_pre = *(const uint4*)(xn + lane * 16), xb_pre = *(const uint4*)(xn + lane * 16 + 8);
.Lbk_loop:
	v_lshl_add_u32 v10, s88, 10, v114
	v_lshl_add_u32 v11, v131, 2, v10
	ds_read2st64_b32 v[0:1], v11 offset1:1
	ds_read2st64_b32 v[2:3], v11 offset0:2 offset1:3
	s_waitcnt lgkmcnt(0)
	v_lshrrev_b32_e32 v4, 12, v0
	v_lshrrev_b32_e32 v5, 12, v1
	s_mov_b32 s89, 0
	v_cmp_eq_u32_e32 vcc, 0, v4
	s_nop 1
	v_mbcnt_lo_u32_b32 v6, vcc_lo, 0
	v_mbcnt_hi_u32_b32 v6, vcc_hi, v6
	s_bcnt1_i32_b64 s90, vcc
	v_add_u32_e32 v6, s89, v6
	v_cndmask_b32_e32 v8, v8, v6, vcc
	s_add_i32 s89, s89, s90
	v_cmp_eq_u32_e32 vcc, 0, v5
	s_nop 1
	v_mbcnt_lo_u32_b32 v7, vcc_lo, 0
	v_mbcnt_hi_u32_b32 v7, vcc_hi, v7
	s_bcnt1_i32_b64 s90, vcc
	v_add_u32_e32 v7, s89, v7
	v_cndmask_b32_e32 v9, v9, v7, vcc
	s_add_i32 s89, s89, s90
	v_cmp_eq_u32_e32 vcc, 1, v4
	s_nop 1
	v_mbcnt_lo_u32_b32 v6, vcc_lo, 0
	v_mbcnt_hi_u32_b32 v6, vcc_hi, v6
	s_bcnt1_i32_b64 s90, vcc
	v_add_u32_e32 v6, s89, v6
	v_cndmask_b32_e32 v8, v8, v6, vcc
	s_add_i32 s89, s89, s90
	v_cmp_eq_u32_e32 vcc, 1, v5
	s_nop 1
	v_mbcnt_lo_u32_b32 v7, vcc_lo, 0
	v_mbcnt_hi_u32_b32 v7, vcc_hi, v7
	s_bcnt1_i32_b64 s90, vcc
	v_add_u32_e32 v7, s89, v7
	v_cndmask_b32_e32 v9, v9, v7, vcc
	s_add_i32 s89, s89, s90
	v_cmp_eq_u32_e32 vcc, 2, v4
	s_nop 1
	v_mbcnt_lo_u32_b32 v6, vcc_lo, 0
	v_mbcnt_hi_u32_b32 v6, vcc_hi, v6
	s_bcnt1_i32_b64 s90, vcc
	v_add_u32_e32 v6, s89, v6
	v_cndmask_b32_e32 v8, v8, v6, vcc
	s_add_i32 s89, s89, s90
	v_cmp_eq_u32_e32 vcc, 2, v5
	s_nop 1
	v_mbcnt_lo_u32_b32 v7, vcc_lo, 0
	v_mbcnt_hi_u32_b32 v7, vcc_hi, v7
	s_bcnt1_i32_b64 s90, vcc
	v_add_u32_e32 v7, s89, v7
	v_cndmask_b32_e32 v9, v9, v7, vcc
	s_add_i32 s89, s89, s90
	v_cmp_eq_u32_e32 vcc, 3, v4
	s_nop 1
	v_mbcnt_lo_u32_b32 v6, vcc_lo, 0
	v_mbcnt_hi_u32_b32 v6, vcc_hi, v6
	s_bcnt1_i32_b64 s90, vcc
	v_add_u32_e32 v6, s89, v6
	v_cndmask_b32_e32 v8, v8, v6, vcc
	s_add_i32 s89, s89, s90
	v_cmp_eq_u32_e32 vcc, 3, v5
	s_nop 1
	v_mbcnt_lo_u32_b32 v7, vcc_lo, 0
	v_mbcnt_hi_u32_b32 v7, vcc_hi, v7
	s_bcnt1_i32_b64 s90, vcc
	v_add_u32_e32 v7, s89, v7
	v_cndmask_b32_e32 v9, v9, v7, vcc
	s_add_i32 s89, s89, s90
	v_lshl_add_u32 v8, v8, 2, v10
	v_lshl_add_u32 v9, v9, 2, v10
	ds_write_b32 v8, v0
	ds_write_b32 v8, v2 offset:512
	ds_write_b32 v9, v1
	ds_write_b32 v9, v3 offset:512
	s_waitcnt lgkmcnt(0)
	s_add_i32 s88, s88, 1
	s_cmp_lt_u32 s88, 8
	s_cbranch_scc1 .Lbk_loop
	s_mul_i32 s16, s85, s22
	v_add_u32_e32 v248, s16, v130
	v_ashrrev_i32_e32 v249, 31, v248
	v_lshlrev_b64 v[248:249], 11, v[248:249]
	v_lshl_add_u64 v[248:249], s[36:37], 0, v[248:249]
	v_lshl_add_u64 v[248:249], v[102:103], 1, v[248:249]
	global_load_dwordx4 v[240:243], v[248:249], off
	global_load_dwordx4 v[244:247], v[248:249], off offset:16
	s_branch .LBB0_1382

; __device__ __forceinline__ void peer_token(const Params& P, int t, int lane, int* sidx, float* sval, const int* sid, const float* sgate, const unsigned* szero) {
;     const bf16_t* xn = (const bf16_t*)(P.ws + WS_XN) + (size_t)t * DM;
;     const uint4 xa_pre = *(const uint4*)(xn + lane * 16), xb_pre = *(const uint4*)(xn + lane * 16 + 8);
;     const float rstd = ((const float*)(P.ws + WS_RSTD))[t];
;     const unsigned char* V = P.ws + WS_V + lane * 8;
;     const float* usc = (const float*)(P.ws + WS_USC);
;     const float* vsc = (const float*)(P.ws + WS_VSC);
;     const int g = lane >> 4, lr = lane & 15;
;     unsigned char* shi = (unsigned char*)sval;
;     unsigned char* slo = (unsigned char*)sidx;
;     {
;         const uint4 xa = xa_pre, xb = xb_pre;
;         const unsigned xw[8] = {xa.x, xa.y, xa.z, xa.w, xb.x, xb.y, xb.z, xb.w};
;         unsigned hi[4], lo[4];
; #pragma unroll
;         for (int i = 0; i < 4; ++i) {
;             const float x0 = bflo(xw[2 * i]), x1 = bfhi(xw[2 * i]), x2 = bflo(xw[2 * i + 1]), x3 = bfhi(xw[2 * i + 1]);
;             int wd = 0;
;             wd = __builtin_amdgcn_cvt_pk_fp8_f32(x0, x1, wd, false);
;             wd = __builtin_amdgcn_cvt_pk_fp8_f32(x2, x3, wd, true);
;             const f32x2 h01 = __builtin_amdgcn_cvt_pk_f32_fp8(wd, false), h23 = __builtin_amdgcn_cvt_pk_f32_fp8(wd, true);
;             int wl = 0;
;             wl = __builtin_amdgcn_cvt_pk_fp8_f32(x0 - h01.x, x1 - h01.y, wl, false);
;             wl = __builtin_amdgcn_cvt_pk_fp8_f32(x2 - h23.x, x3 - h23.y, wl, true);
;             hi[i] = (unsigned)wd; lo[i] = (unsigned)wl;
;         }
;         *(uint4*)(shi + lane * 16) = make_uint4(hi[0], hi[1], hi[2], hi[3]);
;         *(uint4*)(slo + lane * 16) = make_uint4(lo[0], lo[1], lo[2], lo[3]);
;     }
;     __builtin_amdgcn_s_waitcnt(0xc07f);
;     __builtin_amdgcn_wave_barrier();
;     {
;         typedef int v8i __attribute__((ext_vector_type(8)));
;         const unsigned char* Ub = P.ws + WS_U;
;         const unsigned lofs = 64u * (unsigned)(lr >> 3) + 16u * (unsigned)g;
;         const unsigned char* bsrc = (lr < 4) ? (((lr & 2) ? slo : shi) + 128 * (lr & 1) + 16 * g) : (const unsigned char*)szero;
;         const int bstep = (lr < 4) ? 256 : 0, bhalf = (lr < 4) ? 64 : 16;
;         v8i Bv[4];
; #pragma unroll
;         for (int st = 0; st < 4; ++st) {
.LBB0_1382:
	s_mul_i32 s16, s85, s22
	v_add_u32_e32 v112, s16, v130
	v_cmp_gt_i32_e32 vcc, s20, v112
	s_and_saveexec_b64 s[16:17], vcc
	s_cbranch_execz .LBB0_1381
	v_ashrrev_i32_e32 v113, 31, v112
	v_lshlrev_b64 v[0:1], 11, v[112:113]
	v_lshl_add_u64 v[110:111], s[36:37], 0, v[0:1]
	v_lshl_add_u64 v[4:5], v[102:103], 1, v[110:111]
	s_waitcnt vmcnt(0)
	v_mov_b64_e32 v[0:1], v[240:241]
	v_mov_b64_e32 v[2:3], v[242:243]
	v_mov_b64_e32 v[4:5], v[244:245]
	v_mov_b64_e32 v[6:7], v[246:247]
	s_cmp_eq_u32 s85, 7
	s_cbranch_scc1 .Lax_nopf
	s_add_i32 s91, s85, 1
	s_mul_i32 s16, s91, s22
	v_add_u32_e32 v248, s16, v130
	v_ashrrev_i32_e32 v249, 31, v248
	v_lshlrev_b64 v[248:249], 11, v[248:249]
	v_lshl_add_u64 v[248:249], s[36:37], 0, v[248:249]
	v_lshl_add_u64 v[248:249], v[102:103], 1, v[248:249]
	global_load_dwordx4 v[240:243], v[248:249], off
	global_load_dwordx4 v[244:247], v[248:249], off offset:16
.Lax_nopf:
	v_mov_b32_e32 v8, 0
	v_mov_b32_e32 v9, 0
	v_mov_b32_e32 v10, 0
	v_mov_b32_e32 v11, 0
	v_mov_b32_e32 v12, 0
	v_mov_b32_e32 v13, 0
	v_mov_b32_e32 v14, 0
	v_mov_b32_e32 v15, 0
	v_lshl_add_u32 v139, s85, 10, v114
	v_add_u32_e32 v26, v123, v121
	v_add_u32_e32 v27, v124, v121
	v_add_u32_e32 v28, v125, v121
	v_add_u32_e32 v32, v126, v121
	v_lshl_add_u64 v[16:17], v[112:113], 2, s[4:5]
	v_lshl_add_u32 v141, v115, 2, v139
	v_lshlrev_b32_e32 v29, 16, v0
	v_and_b32_e32 v30, 0xffff0000, v0
	v_lshlrev_b32_e32 v34, 16, v2
	v_and_b32_e32 v35, 0xffff0000, v2
	v_lshlrev_b32_e32 v38, 16, v4
	v_and_b32_e32 v39, 0xffff0000, v4
	v_lshlrev_b32_e32 v42, 16, v6
	v_and_b32_e32 v43, 0xffff0000, v6
	v_cvt_pk_fp8_f32 v8, v29, v30
	v_cvt_pk_fp8_f32 v9, v34, v35
	v_cvt_pk_fp8_f32 v10, v38, v39
	v_cvt_pk_fp8_f32 v11, v42, v43
	v_lshlrev_b32_e32 v31, 16, v1
	v_and_b32_e32 v33, 0xffff0000, v1
	v_lshlrev_b32_e32 v36, 16, v3
	v_and_b32_e32 v37, 0xffff0000, v3
	v_lshlrev_b32_e32 v40, 16, v5
	v_and_b32_e32 v41, 0xffff0000, v5
	v_lshlrev_b32_e32 v44, 16, v7
	v_and_b32_e32 v45, 0xffff0000, v7
	v_cvt_pk_fp8_f32 v8, v31, v33 op_sel:[0,0,1]
	v_cvt_pk_fp8_f32 v9, v36, v37 op_sel:[0,0,1]
	v_cvt_pk_fp8_f32 v10, v40, v41 op_sel:[0,0,1]
	v_cvt_pk_fp8_f32 v11, v44, v45 op_sel:[0,0,1]
	v_cvt_pk_f32_fp8_e32 v[0:1], v8
	v_cvt_pk_f32_fp8_e32 v[4:5], v9
	v_cvt_pk_f32_fp8_e32 v[18:19], v10
	v_cvt_pk_f32_fp8_e32 v[22:23], v11
	v_cvt_pk_f32_fp8_sdwa v[2:3], v8 src0_sel:WORD_1
	v_cvt_pk_f32_fp8_sdwa v[6:7], v9 src0_sel:WORD_1
	v_cvt_pk_f32_fp8_sdwa v[20:21], v10 src0_sel:WORD_1
	v_cvt_pk_f32_fp8_sdwa v[24:25], v11 src0_sel:WORD_1
	v_sub_f32_e32 v0, v29, v0
	v_sub_f32_e32 v1, v30, v1
	v_sub_f32_e32 v4, v34, v4
	v_sub_f32_e32 v5, v35, v5
	v_sub_f32_e32 v18, v38, v18
	v_sub_f32_e32 v19, v39, v19
	v_sub_f32_e32 v22, v42, v22
	v_sub_f32_e32 v23, v43, v23
	v_cvt_pk_fp8_f32 v12, v0, v1
	v_cvt_pk_fp8_f32 v13, v4, v5
	v_cvt_pk_fp8_f32 v14, v18, v19
	v_cvt_pk_fp8_f32 v15, v22, v23
	v_sub_f32_e32 v2, v31, v2
	v_sub_f32_e32 v3, v33, v3
	v_sub_f32_e32 v6, v36, v6
	v_sub_f32_e32 v7, v37, v7
	v_sub_f32_e32 v20, v40, v20
	v_sub_f32_e32 v21, v41, v21
	v_sub_f32_e32 v24, v44, v24
	v_sub_f32_e32 v25, v45, v25
	v_cvt_pk_fp8_f32 v12, v2, v3 op_sel:[0,0,1]
	v_cvt_pk_fp8_f32 v13, v6, v7 op_sel:[0,0,1]
	v_cvt_pk_fp8_f32 v14, v20, v21 op_sel:[0,0,1]
	v_cvt_pk_fp8_f32 v15, v24, v25 op_sel:[0,0,1]
	ds_write_b128 v119, v[8:11] offset:9216
	ds_write_b128 v119, v[12:15] offset:8192
	s_waitcnt lgkmcnt(0)
	s_and_b32 s90, s85, 3
	s_cmp_eq_u32 s90, 1
	s_cbranch_scc1 .Lbs1
	s_cmp_eq_u32 s90, 2
	s_cbranch_scc1 .Lbs2
	s_cmp_eq_u32 s90, 3
	s_cbranch_scc1 .Lbs3
	ds_read_b128 v[162:165], v150
	ds_read_b128 v[166:169], v151
	ds_read_b128 v[170:173], v152
	ds_read_b128 v[174:177], v153
	s_branch .Lbs_join

; __global__ void __launch_bounds__(256, 2) mega(Params P) {
	.amdhsa_kernel _ZN12_GLOBAL__N_14megaENS_6ParamsE
		.amdhsa_group_segment_fixed_size 0
		.amdhsa_private_segment_fixed_size 0
		.amdhsa_kernarg_size 408
		.amdhsa_user_sgpr_count 2
		.amdhsa_user_sgpr_dispatch_ptr 0
		.amdhsa_user_sgpr_queue_ptr 0
		.amdhsa_user_sgpr_kernarg_segment_ptr 1
		.amdhsa_user_sgpr_dispatch_id 0
		.amdhsa_user_sgpr_kernarg_preload_length 0
		.amdhsa_user_sgpr_kernarg_preload_offset 0
		.amdhsa_user_sgpr_private_segment_size 0
		.amdhsa_uses_dynamic_stack 0
		.amdhsa_enable_private_segment 0
		.amdhsa_system_sgpr_workgroup_id_x 1
		.amdhsa_system_sgpr_workgroup_id_y 0
		.amdhsa_system_sgpr_workgroup_id_z 0
		.amdhsa_system_sgpr_workgroup_info 0
		.amdhsa_system_vgpr_workitem_id 0
		.amdhsa_next_free_vgpr 256
		.amdhsa_next_free_sgpr 98
		.amdhsa_accum_offset 256
		.amdhsa_reserve_vcc 1
		.amdhsa_float_round_mode_32 0
		.amdhsa_float_round_mode_16_64 0
		.amdhsa_float_denorm_mode_32 3
		.amdhsa_float_denorm_mode_16_64 3
		.amdhsa_dx10_clamp 1
		.amdhsa_ieee_mode 1
		.amdhsa_fp16_overflow 0
		.amdhsa_tg_split 0
		.amdhsa_exception_fp_ieee_invalid_op 0
		.amdhsa_exception_fp_denorm_src 0
		.amdhsa_exception_fp_ieee_div_zero 0
		.amdhsa_exception_fp_ieee_overflow 0
		.amdhsa_exception_fp_ieee_underflow 0
		.amdhsa_exception_fp_ieee_inexact 0
		.amdhsa_exception_int_div_zero 0
	.end_amdhsa_kernel

; __global__ void __launch_bounds__(256, 2) mega(Params P) {
amdhsa.kernels:
  - .agpr_count:     0
    .args:
      - .offset:         0
        .size:           152
        .value_kind:     by_value
      - .offset:         152
        .size:           4
        .value_kind:     hidden_block_count_x
      - .offset:         156
        .size:           4
        .value_kind:     hidden_block_count_y
      - .offset:         160
        .size:           4
        .value_kind:     hidden_block_count_z
      - .offset:         164
        .size:           2
        .value_kind:     hidden_group_size_x
      - .offset:         166
        .size:           2
        .value_kind:     hidden_group_size_y
      - .offset:         168
        .size:           2
        .value_kind:     hidden_group_size_z
      - .offset:         170
        .size:           2
        .value_kind:     hidden_remainder_x
      - .offset:         172
        .size:           2
        .value_kind:     hidden_remainder_y
      - .offset:         174
        .size:           2
        .value_kind:     hidden_remainder_z
      - .offset:         192
        .size:           8
        .value_kind:     hidden_global_offset_x
      - .offset:         200
        .size:           8
        .value_kind:     hidden_global_offset_y
      - .offset:         208
        .size:           8
        .value_kind:     hidden_global_offset_z
      - .offset:         216
        .size:           2
        .value_kind:     hidden_grid_dims
      - .offset:         272
        .size:           4
        .value_kind:     hidden_dynamic_lds_size
    .group_segment_fixed_size: 0
    .kernarg_segment_align: 8
    .kernarg_segment_size: 408
    .language:       OpenCL C
    .language_version:
      - 2
      - 0
    .max_flat_workgroup_size: 256
    .name:           _ZN12_GLOBAL__N_14megaENS_6ParamsE
    .private_segment_fixed_size: 0
    .sgpr_count:     104
    .sgpr_spill_count: 84
    .symbol:         _ZN12_GLOBAL__N_14megaENS_6ParamsE.kd
    .uniform_work_group_size: 1
    .uses_dynamic_stack: false
    .vgpr_count:     256
    .vgpr_spill_count: 0
    .wavefront_size: 64
